# kernel entry: the three serialized kernarg scalar loads (0x80/0x90, 0x00, 0x40) issued together with one wait (prologue de-serialisation at kernel start)
# speedup vs baseline: 1.0033x; 1.0033x over previous
; #define LAS __attribute__((address_space(3)))
; __global__ void __launch_bounds__(NWAVES * 64, 2) mk_fwd(Args args) {
;     extern __shared__ __attribute__((aligned(16))) unsigned char lds_raw[];
;     LAS unsigned char* lds = (LAS unsigned char*)lds_raw;
;     volatile LAS unsigned* MISC = (volatile LAS unsigned*)(lds + MISC_OFF);
;     const int tid = threadIdx.x, wave = __builtin_amdgcn_readfirstlane(tid >> 6);
;     ...
;     const int G = gridDim.x; int vcu; { const int bx = blockIdx.x; vcu = (G % 8 == 0) ? (bx % 8) * (G / 8) + bx / 8 : bx; }
;     unsigned char* ws = args.ws;
;     unsigned* ctl = (unsigned*)(ws + WS_CTL);
;     float* ssq = (float*)(ctl + CW_SSQ);
;     ...
;     LAS float* rtab = (LAS float*)(lds + LDSCTL_OFF + 1024);
;     ...
;     float* out = args.out;
;     bf16* HB = (bf16*)(ws + WS_HB); bf16* DA = (bf16*)(ws + WS_DA); bf16* MG = (bf16*)(ws + WS_MG); bf16* PROJ = (bf16*)(ws + WS_PROJ); bf16* ACT = PROJ;
;     for (int u = tid; u < (LDS_BYTES - LDSCTL_OFF) / 4; u += NWAVES * 64) ((LAS unsigned*)(lds + LDSCTL_OFF))[u] = 0u;
_Z6mk_fwd4Args:
	s_mov_b32 s101, 0
	s_load_dword s96, s[0:1], 0x90
	s_load_dwordx2 s[4:5], s[0:1], 0x80
	s_load_dwordx16 s[8:23], s[0:1], 0x0
	s_load_dwordx16 s[36:51], s[0:1], 0x40
	v_readfirstlane_b32 s33, v0
	s_waitcnt lgkmcnt(0)
	v_writelane_b32 v242, s4, 0
	s_nop 1
	v_writelane_b32 v242, s5, 1
	s_add_u32 s4, s0, 0x90
	s_addc_u32 s5, s1, 0
	v_writelane_b32 v242, s4, 2
	s_nop 1
	v_writelane_b32 v242, s5, 3
	s_and_b32 s5, s96, 7
	s_mov_b32 s4, 0
	s_cmp_lg_u32 s5, 0
	v_writelane_b32 v242, s2, 4
	v_writelane_b32 v242, s2, 5
	s_cbranch_scc1 .LBB0_2
	v_readlane_b32 s2, v242, 4
	s_ashr_i32 s6, s2, 31
	s_lshr_b32 s6, s6, 29
	s_add_i32 s6, s2, s6
	s_and_b32 s7, s6, -8
	s_ashr_i32 s5, s96, 3
	s_sub_i32 s7, s2, s7
	s_mul_i32 s5, s5, s7
	s_ashr_i32 s6, s6, 3
	s_add_i32 s5, s5, s6
	v_writelane_b32 v242, s5, 5
.LBB0_2:
	v_lshl_add_u32 v1, v0, 2, 0
	v_add_u32_e32 v1, 0x21800, v1
	s_mov_b32 s5, 1
	v_mov_b32_e32 v2, 0
	s_waitcnt lgkmcnt(0)
	v_writelane_b32 v242, s8, 6
	s_mov_b32 s6, s4
	s_nop 0
	v_writelane_b32 v242, s9, 7
	v_writelane_b32 v242, s10, 8
	v_writelane_b32 v242, s11, 9
	v_writelane_b32 v242, s12, 10
	v_writelane_b32 v242, s13, 11
	v_writelane_b32 v242, s14, 12
	v_writelane_b32 v242, s15, 13
	v_writelane_b32 v242, s16, 14
	v_writelane_b32 v242, s17, 15
	v_writelane_b32 v242, s18, 16
	v_writelane_b32 v242, s19, 17
	v_writelane_b32 v242, s20, 18
	v_writelane_b32 v242, s21, 19
	v_writelane_b32 v242, s22, 20
	v_writelane_b32 v242, s23, 21
	s_mov_b64 s[0:1], 0
	s_waitcnt lgkmcnt(0)
	v_writelane_b32 v242, s36, 22
	s_nop 1
	v_writelane_b32 v242, s37, 23
	v_writelane_b32 v242, s38, 24
	v_writelane_b32 v242, s39, 25
	v_writelane_b32 v242, s40, 26
	v_writelane_b32 v242, s41, 27
	v_writelane_b32 v242, s42, 28
	v_writelane_b32 v242, s43, 29
	v_writelane_b32 v242, s44, 30
	v_writelane_b32 v242, s45, 31
	v_writelane_b32 v242, s46, 32
	v_writelane_b32 v242, s47, 33
	v_writelane_b32 v242, s48, 34
	v_writelane_b32 v242, s49, 35
	v_writelane_b32 v242, s50, 36
	v_writelane_b32 v242, s51, 37
	s_branch .LBB0_4
